# sync points 80/104
# baseline (speedup 1.0000x reference)
; template <bool INSYNC> DI void mlstm_phase(const Ctx& C, const bf16* PROJ, const f32x4* TAB, const bf16* PP, bf16* HF, bf16* HB, const XcdBarrier& xbar) {
;     ...
;         for (int c = 0; c < SEQ / 64; ++c) {
;             if (INSYNC && (c == 43 || c == 86)) xcd_barrier(xbar);
.LBB0_1403:
	s_mov_b32 s35, s22
	s_cmpk_lt_i32 s22, 0x68
	s_cbranch_scc1 .LBB0_1405
	s_cmpk_eq_i32 s35, 0x68
	s_cselect_b64 s[20:21], -1, 0
	s_cbranch_execz .LBB0_1406
	s_branch .LBB0_1407

; template <bool INSYNC> DI void mlstm_phase(const Ctx& C, const bf16* PROJ, const f32x4* TAB, const bf16* PP, bf16* HF, bf16* HB, const XcdBarrier& xbar) {
;     ...
;             if (INSYNC && (c == 43 || c == 86)) xcd_barrier(xbar);
.LBB0_1406:
	s_cmp_eq_u32 s35, 80
	s_cselect_b64 s[20:21], -1, 0
